# up GEMM: LDS-DMA pieces cover whole 128-B lines (8 rows x 128 B, XOR-swizzled chunks) instead of half lines; plus static prio
# baseline (speedup 1.0000x reference)
; #define PG8_STAGE(bufoff, gbase, voff) do { _Pragma("unroll") for (int _i = 0; _i < 2; ++_i) \
;         __builtin_amdgcn_global_load_lds((const unsigned*)((const char*)(gbase) + (voff)[_i]), (PG8_LAS unsigned*)(lds + (bufoff) + ldsw + _i * 8192), 16, 0, 0); } while (0)
; template <class Epi, class Sched, bool ALIGN_EPI = false, bool SP2 = false>
; __device__ __forceinline__ void gemm_phase(PG8_LAS unsigned char* lds, const Gemm g, const Sched& S, const Epi& E, int wid_in) {
;     ...
;     for (int i = 0; i < 2; ++i) { int R, C; stage_rc(tid * 16 + i * 8192, R, C); const int Rb = Epi::PERM ? ((R & ~31) + perm32(R & 31)) : R;
;         voffA[i] = (unsigned)(R * K + C) * 2u; voffB[i] = (unsigned)(Rb * K + C) * 2u; }
;     ...
;     if constexpr (SP2) {
;         PG8_STAGE(PG8_SB(0, 0), cB, voffB); PG8_STAGE(PG8_SB(0, 1), cB + hstep, voffB); PG8_STAGE(PG8_SA(0, 0), cA, voffA); PG8_STAGE(PG8_SA(0, 1), cA + hstep, voffA);
.LBB0_1143:
	s_andn2_b64 vcc, exec, s[8:9]
	s_cbranch_vccnz .LBB0_1208
	v_readlane_b32 s0, v254, 0
	v_readlane_b32 s1, v254, 1
	s_load_dwordx4 s[12:15], s[0:1], 0xd0
	v_readlane_b32 s0, v255, 2
	v_readlane_b32 s1, v255, 3
	s_waitcnt lgkmcnt(0)
	s_mov_b32 s10, s91
	s_andn2_b64 vcc, exec, s[0:1]
	s_mov_b64 s[8:9], s[14:15]
	v_mbcnt_lo_u32_b32 v16, -1, 0
	v_mbcnt_hi_u32_b32 v16, -1, v16
	s_cbranch_vccnz .LBB0_1160
	v_lshl_add_u32 v0, v16, 4, s59
	v_add_u32_e32 v2, 0x2000, v0
	v_ashrrev_i32_e32 v3, 31, v2
	v_lshrrev_b32_e32 v3, 22, v3
	v_add_u32_e32 v3, v2, v3
	v_ashrrev_i32_e32 v10, 10, v3
	v_mul_i32_i24_e32 v3, 0x400, v10
	v_sub_u32_e32 v2, v2, v3
	v_lshrrev_b32_e32 v3, 4, v2
	v_bitop3_b32 v2, v3, v2, 32 bitop3:0x6c
	s_add_u32 s0, s8, 0x1eb00000
	v_ashrrev_i32_e32 v3, 31, v2
	s_addc_u32 s1, s9, 0
	s_ashr_i32 s11, s10, 31
	v_lshrrev_b32_e32 v3, 26, v3
	s_lshl_b64 s[10:11], s[10:11], 25
	v_add_u32_e32 v3, v2, v3
	v_lshlrev_b32_e32 v4, 3, v10
	s_add_u32 s10, s8, s10
	v_ashrrev_i32_e32 v11, 6, v3
	v_and_b32_e32 v4, -16, v4
	v_and_b32_e32 v3, 0xffc0, v3
	s_addc_u32 s11, s9, s11
	v_add_u32_e32 v4, v11, v4
	v_sub_u32_e32 v2, v2, v3
	s_add_u32 s30, s10, 0xe500000
	v_and_b32_e32 v5, 3, v11
	s_mov_b32 s10, 0xfffe0
	v_lshrrev_b32_e32 v6, 2, v4
	v_lshlrev_b32_e32 v7, 1, v4
	v_lshrrev_b16_e32 v3, 7, v2
	v_and_or_b32 v5, v4, s10, v5
	v_and_b32_e32 v6, 4, v6
	v_and_b32_e32 v7, 24, v7
	v_and_b32_e32 v3, 1, v3
	v_or3_b32 v5, v5, v6, v7
	v_add_u16_e32 v2, v2, v3
	v_mov_b32_e32 v7, 1
	v_lshlrev_b32_e32 v6, 5, v10
	v_ashrrev_i16_sdwa v2, v7, sext(v2) dst_sel:DWORD dst_unused:UNUSED_PAD src0_sel:DWORD src1_sel:BYTE_0
	v_and_b32_e32 v6, 32, v6
	v_bfe_i32 v12, v2, 0, 16
	v_add_lshl_u32 v2, v6, v12, 1
	v_lshl_add_u32 v130, v5, 12, v2
	v_lshl_add_u32 v132, v4, 12, v2
	v_ashrrev_i32_e32 v2, 31, v0
	v_lshrrev_b32_e32 v2, 22, v2
	v_add_u32_e32 v2, v0, v2
	v_ashrrev_i32_e32 v13, 10, v2
	v_mul_i32_i24_e32 v2, 0x400, v13
	v_sub_u32_e32 v0, v0, v2
	v_lshrrev_b32_e32 v2, 4, v0
	v_bitop3_b32 v0, v2, v0, 32 bitop3:0x6c
	v_ashrrev_i32_e32 v2, 31, v0
	v_lshrrev_b32_e32 v2, 26, v2
	v_add_u32_e32 v2, v0, v2
	v_lshlrev_b32_e32 v3, 3, v13
	v_ashrrev_i32_e32 v14, 6, v2
	v_and_b32_e32 v3, -16, v3
	v_add_u32_e32 v3, v14, v3
	v_and_b32_e32 v4, 3, v14
	s_addc_u32 s31, s11, 0
	s_ashr_i32 s14, s47, 2
	v_and_or_b32 v4, v3, s10, v4
	v_lshrrev_b32_e32 v5, 2, v3
	v_lshlrev_b32_e32 v6, 1, v3
	v_and_b32_e32 v2, 0xc0, v2
	v_readlane_b32 s10, v255, 21
	v_and_b32_e32 v5, 4, v5
	v_and_b32_e32 v6, 24, v6
	v_sub_u32_e32 v0, v0, v2
	v_readlane_b32 s11, v255, 22
	s_add_u32 s24, s0, s10
	v_or3_b32 v4, v4, v5, v6
	v_lshlrev_b32_e32 v5, 5, v13
	v_ashrrev_i16_sdwa v0, v7, sext(v0) dst_sel:DWORD dst_unused:UNUSED_PAD src0_sel:DWORD src1_sel:BYTE_0
	s_addc_u32 s25, s1, s11
	v_readlane_b32 s10, v255, 17
	v_and_b32_e32 v5, 32, v5
	v_bfe_i32 v15, v0, 0, 16
	v_readlane_b32 s11, v255, 18
	s_add_u32 s26, s30, s10
	v_add_lshl_u32 v2, v5, v15, 1
	s_addc_u32 s27, s31, s11
	s_add_i32 s34, s59, 0
	v_lshl_add_u32 v0, v4, 12, v2
	s_add_i32 m0, s34, 0x10000
	v_lshl_add_u32 v134, v3, 12, v2
	v_mbcnt_lo_u32_b32 v230, -1, 0
	v_mbcnt_hi_u32_b32 v230, -1, v230
	v_lshrrev_b32_e32 v231, 3, v230
	v_and_b32_e32 v234, 7, v231
	v_and_b32_e32 v235, 7, v230
	v_xor_b32_e32 v235, v235, v234
	v_lshlrev_b32_e32 v235, 4, v235
	s_lshl_b32 s98, s47, 3
	v_add_u32_e32 v234, s98, v231
	v_lshl_add_u32 v134, v234, 12, v235
	v_add_u32_e32 v132, 0x40000, v134
	s_and_b32 s98, s47, 1
	s_lshl_b32 s98, s98, 4
	s_bfe_u32 s99, s47, 0x10001
	s_lshl_b32 s99, s99, 2
	s_add_u32 s98, s98, s99
	s_lshr_b32 s99, s47, 2
	s_lshl_b32 s99, s99, 5
	s_add_u32 s98, s98, s99
	v_lshrrev_b32_e32 v234, 5, v230
	v_lshlrev_b32_e32 v234, 3, v234
	v_and_b32_e32 v231, 3, v231
	v_add3_u32 v234, v234, v231, s98
	v_lshl_add_u32 v0, v234, 12, v235
	v_add_u32_e32 v130, 0x40000, v0
	global_load_lds_dwordx4 v0, s[26:27]
	s_add_i32 m0, s34, 0x12000
	s_add_u32 s10, s26, 0x80000
	global_load_lds_dwordx4 v130, s[26:27]
	s_addc_u32 s11, s27, 0
	s_add_i32 m0, s34, 0x14000
	s_add_i32 s35, s34, 0x2000
	global_load_lds_dwordx4 v0, s[10:11]
	s_add_i32 m0, s34, 0x16000
	v_mov_b32_e32 v131, v1
	global_load_lds_dwordx4 v130, s[10:11]
	s_mov_b32 m0, s34
	s_add_u32 s10, s24, 0x80000
	global_load_lds_dwordx4 v134, s[24:25]
	s_mov_b32 m0, s35
	s_addc_u32 s11, s25, 0
	s_add_i32 s36, s34, 0x4000
	global_load_lds_dwordx4 v132, s[24:25]
	s_mov_b32 m0, s36
	s_add_i32 s37, s34, 0x6000
	global_load_lds_dwordx4 v134, s[10:11]
	s_mov_b32 m0, s37
	v_mov_b32_e32 v135, v1
	global_load_lds_dwordx4 v132, s[10:11]
	v_mov_b32_e32 v133, v1
	s_cmp_eq_u32 s14, 1
	v_lshl_add_u64 v[8:9], s[26:27], 0, v[0:1]
	v_lshl_add_u64 v[6:7], s[26:27], 0, v[130:131]
	v_lshl_add_u64 v[2:3], s[24:25], 0, v[134:135]
	s_cselect_b64 s[10:11], -1, 0
	s_cmp_lg_u32 s14, 1
	v_lshl_add_u64 v[4:5], s[24:25], 0, v[132:133]
	s_cbranch_scc1 .LBB0_1147
	s_barrier
; #define PG8_STAGE(bufoff, gbase, voff) do { _Pragma("unroll") for (int _i = 0; _i < 2; ++_i) \
;         __builtin_amdgcn_global_load_lds((const unsigned*)((const char*)(gbase) + (voff)[_i]), (PG8_LAS unsigned*)(lds + (bufoff) + ldsw + _i * 8192), 16, 0, 0); } while (0)
; #define PG8_WAIT_V(n) asm volatile("s_waitcnt vmcnt(" #n ")" ::: "memory")
; #define PG8_BAR __builtin_amdgcn_s_barrier()
; template <class Epi, class Sched, bool ALIGN_EPI = false, bool SP2 = false>
; __device__ __forceinline__ void gemm_phase(PG8_LAS unsigned char* lds, const Gemm g, const Sched& S, const Epi& E, int wid_in) {
;     ...
;     const int aoff = lds_byte(wr * 64 + fr, fq * 8), boff = lds_byte(wc * 32 + fr, fq * 8);
;     ...
;         if (wr == 1) PG8_BAR;
;         PG8_WAIT_V(2); PG8_BAR;
;         PG8_STAGE(PG8_SB(1, 0), cB + kstep, voffB); PG8_STAGE(PG8_SA(1, 0), cA + kstep, voffA); PG8_STAGE(PG8_SB(1, 1), cB + hstep + kstep, voffB);
;         PG8_WAIT_V(6); PG8_BAR;
.LBB0_1147:
	s_add_u32 s12, s8, 0x23000000
	v_and_b32_e32 v18, 48, v16
	v_lshlrev_b32_e32 v20, 6, v16
	s_movk_i32 s8, 0x3c0
	s_addc_u32 s13, s9, 0
	v_and_or_b32 v18, v20, s8, v18
	s_lshl_b32 s8, s47, 5
	s_and_b32 s39, s8, 0x60
	s_add_i32 m0, s34, 0x18000
	v_lshl_add_u64 v[8:9], v[8:9], 0, s[94:95]
	s_lshl_b32 s38, s14, 6
	v_ashrrev_i32_e32 v17, 6, v16
	s_lshr_b32 s8, s39, 3
	s_waitcnt vmcnt(2)
	s_barrier
	global_load_lds_dwordx4 v[8:9], off
	v_lshl_add_u64 v[6:7], v[6:7], 0, s[94:95]
	s_add_i32 m0, s34, 0x1a000
	s_add_i32 s48, s34, 0x8000
	s_add_i32 s52, s34, 0xa000
	v_lshlrev_b32_e32 v19, 10, v17
	v_add_lshl_u32 v17, s8, v17, 10
	global_load_lds_dwordx4 v[6:7], off
	v_lshl_add_u64 v[2:3], v[2:3], 0, s[94:95]
	s_mov_b32 m0, s48
	s_add_u32 s8, s26, 0x80080
	global_load_lds_dwordx4 v[2:3], off
	v_lshl_add_u64 v[2:3], v[4:5], 0, s[94:95]
	s_mov_b32 m0, s52
	s_addc_u32 s9, s27, 0
	global_load_lds_dwordx4 v[2:3], off
	s_add_i32 m0, s34, 0x1c000
	v_lshl_add_u64 v[2:3], s[8:9], 0, v[0:1]
	global_load_lds_dwordx4 v[2:3], off
	v_lshl_add_u64 v[2:3], s[8:9], 0, v[130:131]
	s_add_i32 m0, s34, 0x1e000
	v_lshlrev_b32_e32 v16, 2, v16
	global_load_lds_dwordx4 v[2:3], off
	v_lshlrev_b32_e32 v2, 15, v10
	v_and_b32_e32 v2, 0xffff0000, v2
	v_lshl_add_u32 v2, v11, 12, v2
	v_and_b32_e32 v3, 1, v10
	v_lshl_or_b32 v2, v3, 6, v2
	v_lshl_add_u32 v136, v12, 1, v2
	v_lshlrev_b32_e32 v2, 15, v13
	v_and_b32_e32 v2, 0xffff0000, v2
	v_lshl_add_u32 v19, s14, 13, v19
	v_and_b32_e32 v16, 32, v16
	s_waitcnt vmcnt(6)
	v_lshl_add_u32 v2, v14, 12, v2
	v_and_b32_e32 v3, 1, v13
	v_bitop3_b32 v19, v18, v19, v16 bitop3:0xde
	s_cmp_lt_u32 s47, 4
	v_lshl_or_b32 v2, v3, 6, v2
	v_readlane_b32 s8, v255, 19
	v_bitop3_b32 v142, v17, v18, v16 bitop3:0xf6
	s_cselect_b64 s[14:15], -1, 0
	v_mov_b32_e32 v137, v1
	v_lshl_add_u32 v138, v15, 1, v2
	v_mov_b32_e32 v139, v1
	s_mov_b32 s53, 0
	v_add_u32_e32 v143, 0, v19
	v_readlane_b32 s62, v255, 16
	s_mov_b32 s61, s8
	s_barrier
	v_readlane_b32 s9, v255, 20
	v_mov_b32_e32 v138, v134
	v_mov_b32_e32 v136, v132
	v_mbcnt_lo_u32_b32 v230, -1, 0
	v_mbcnt_hi_u32_b32 v230, -1, v230
	v_and_b32_e32 v231, 15, v230
	v_lshrrev_b32_e32 v234, 4, v230
	v_and_b32_e32 v235, 7, v231
	v_xor_b32_e32 v234, v234, v235
	v_xor_b32_e32 v235, 4, v234
	v_lshlrev_b32_e32 v234, 4, v234
	v_lshlrev_b32_e32 v235, 4, v235
	s_lshr_b32 s98, s47, 2
	s_lshl_b32 s98, s98, 6
	v_add_u32_e32 v143, s98, v231
	v_lshlrev_b32_e32 v143, 7, v143
	v_add_u32_e32 v232, v143, v235
	v_add_u32_e32 v143, v143, v234
	s_and_b32 s98, s47, 3
	s_lshl_b32 s98, s98, 5
	v_add_u32_e32 v142, s98, v231
	v_lshlrev_b32_e32 v142, 7, v142
	v_add_u32_e32 v233, v142, v235
	v_add_u32_e32 v142, v142, v234
	s_branch .LBB0_1150

; #define PG8_STAGE(bufoff, gbase, voff) do { _Pragma("unroll") for (int _i = 0; _i < 2; ++_i) \
;         __builtin_amdgcn_global_load_lds((const unsigned*)((const char*)(gbase) + (voff)[_i]), (PG8_LAS unsigned*)(lds + (bufoff) + ldsw + _i * 8192), 16, 0, 0); } while (0)
; #define PG8_LDA(dst, b, h) do { _Pragma("unroll") for (int m = 0; m < 4; ++m) _Pragma("unroll") for (int k = 0; k < 2; ++k) dst[m][k] = *(const PG8_LAS bf16x8*)(lds + PG8_SA(b, h) + aoff + m * 2048 + k * 1024); } while (0)
; #define PG8_LDB(dst, b, h) do { _Pragma("unroll") for (int n = 0; n < 2; ++n) _Pragma("unroll") for (int k = 0; k < 2; ++k) dst[n][k] = *(const PG8_LAS bf16x8*)(lds + PG8_SB(b, h) + boff + n * 2048 + k * 1024); } while (0)
; #define PG8_MMA(ai, bj, At, Bt) do { __builtin_amdgcn_s_setprio(1); _Pragma("unroll") for (int m = 0; m < 4; ++m) _Pragma("unroll") for (int n = 0; n < 2; ++n) _Pragma("unroll") for (int k = 0; k < 2; ++k) \
;         acc[ai][bj][m][n] = __builtin_amdgcn_mfma_f32_16x16x32_bf16(Bt[n][k], At[m][k], acc[ai][bj][m][n], 0, 0, 0); __builtin_amdgcn_s_setprio(0); } while (0)
; #define PG8_WAIT_V(n) asm volatile("s_waitcnt vmcnt(" #n ")" ::: "memory")
; #define PG8_BAR __builtin_amdgcn_s_barrier()
; template <class Epi, class Sched, bool ALIGN_EPI = false, bool SP2 = false>
; __device__ __forceinline__ void gemm_phase(PG8_LAS unsigned char* lds, const Gemm g, const Sched& S, const Epi& E, int wid_in) {
;     ...
;         for (int t = 0; t < nt; t += 2) {
;             const bool last = (t == nt - 2);
;             const char* a1 = cA + (size_t)(t + 1) * kstep;
;             const char* a2 = last ? nA : cA + (size_t)(t + 2) * kstep; const char* b2 = last ? nB : cB + (size_t)(t + 2) * kstep;
;             const char* a3 = a2 + kstep; const char* b3 = b2 + kstep;
;             if (last && has_next) S.a_ready(nxt);
;             if constexpr (SP2) {
;             PG8_LDB(B0, 0, 0); PG8_LDB(B1, 0, 1); PG8_SCHED; PG8_LDA(At, 0, 0); PG8_STAGE(PG8_SA(1, 1), a1 + hstep, voffA);
;             PG8_WAIT_V(8); PG8_WAIT_L(0); PG8_BAR; PG8_MMA(0, 0, At, B0); PG8_MMA(0, 1, At, B1); PG8_BAR; PG8_SCHED;
;             PG8_LDA(At, 0, 1); PG8_STAGE(PG8_SB(0, 0), b2, voffB); PG8_STAGE(PG8_SB(0, 1), b2 + hstep, voffB); PG8_STAGE(PG8_SA(0, 0), a2, voffA);
;             PG8_WAIT_V(8); PG8_WAIT_L(0); PG8_BAR; PG8_MMA(1, 0, At, B0); PG8_MMA(1, 1, At, B1); PG8_BAR; PG8_SCHED;
.Lprio_skip_4:
.LBB0_1153:
	s_add_u32 s26, s24, 0xfff80080
	s_addc_u32 s27, s25, -1
	s_add_i32 s40, 0, 0x10000
	s_cmp_eq_u32 s73, 28
	s_cselect_b32 s29, s19, s27
	s_cselect_b32 s28, s64, s26
	v_add_u32_e32 v140, s40, v142
	v_add_u32_e32 v234, s40, v233
	s_cselect_b32 s27, s17, s63
	s_cselect_b32 s26, s65, s72
	s_add_i32 s42, 0, 0x14000
	ds_read_b128 v[144:147], v140
	ds_read_b128 v[148:151], v234
	ds_read_b128 v[152:155], v140 offset:2048
	ds_read_b128 v[156:159], v234 offset:2048
	v_add_u32_e32 v140, s42, v142
	v_add_u32_e32 v234, s42, v233
	ds_read_b128 v[160:163], v140
	ds_read_b128 v[164:167], v234
	ds_read_b128 v[168:171], v140 offset:2048
	ds_read_b128 v[172:175], v234 offset:2048
	v_lshl_add_u64 v[140:141], s[24:25], 0, v[138:139]
	s_add_i32 m0, s34, 0xc000
	ds_read_b128 v[176:179], v143
	ds_read_b128 v[180:183], v232
	ds_read_b128 v[184:187], v143 offset:2048
	ds_read_b128 v[188:191], v232 offset:2048
	ds_read_b128 v[208:211], v143 offset:4096
	ds_read_b128 v[212:215], v232 offset:4096
	ds_read_b128 v[216:219], v143 offset:6144
	ds_read_b128 v[220:223], v232 offset:6144
	global_load_lds_dwordx4 v[140:141], off
	v_lshl_add_u64 v[140:141], s[24:25], 0, v[136:137]
	s_add_i32 m0, s34, 0xe000
	s_nop 0
	global_load_lds_dwordx4 v[140:141], off
	s_waitcnt vmcnt(8)
	s_waitcnt lgkmcnt(0)
	s_barrier
	s_waitcnt lgkmcnt(0)
	v_mfma_f32_16x16x32_bf16 v[126:129], v[144:147], v[176:179], v[126:129]
	v_mfma_f32_16x16x32_bf16 v[122:125], v[152:155], v[176:179], v[122:125]
	v_mfma_f32_16x16x32_bf16 v[110:113], v[144:147], v[184:187], v[110:113]
	v_mfma_f32_16x16x32_bf16 v[106:109], v[152:155], v[184:187], v[106:109]
	v_mfma_f32_16x16x32_bf16 v[94:97], v[144:147], v[208:211], v[94:97]
	v_mfma_f32_16x16x32_bf16 v[90:93], v[152:155], v[208:211], v[90:93]
	v_mfma_f32_16x16x32_bf16 v[78:81], v[144:147], v[216:219], v[78:81]
	v_mfma_f32_16x16x32_bf16 v[74:77], v[152:155], v[216:219], v[74:77]
	v_mfma_f32_16x16x32_bf16 v[126:129], v[148:151], v[180:183], v[126:129]
	v_mfma_f32_16x16x32_bf16 v[122:125], v[156:159], v[180:183], v[122:125]
	v_mfma_f32_16x16x32_bf16 v[110:113], v[148:151], v[188:191], v[110:113]
	v_mfma_f32_16x16x32_bf16 v[106:109], v[156:159], v[188:191], v[106:109]
	v_mfma_f32_16x16x32_bf16 v[94:97], v[148:151], v[212:215], v[94:97]
	v_mfma_f32_16x16x32_bf16 v[90:93], v[156:159], v[212:215], v[90:93]
	v_mfma_f32_16x16x32_bf16 v[78:81], v[148:151], v[220:223], v[78:81]
	v_mfma_f32_16x16x32_bf16 v[74:77], v[156:159], v[220:223], v[74:77]
	v_mfma_f32_16x16x32_bf16 v[118:121], v[160:163], v[176:179], v[118:121]
	v_mfma_f32_16x16x32_bf16 v[114:117], v[168:171], v[176:179], v[114:117]
	v_mfma_f32_16x16x32_bf16 v[102:105], v[160:163], v[184:187], v[102:105]
	v_mfma_f32_16x16x32_bf16 v[98:101], v[168:171], v[184:187], v[98:101]
	v_mfma_f32_16x16x32_bf16 v[86:89], v[160:163], v[208:211], v[86:89]
	v_mfma_f32_16x16x32_bf16 v[82:85], v[168:171], v[208:211], v[82:85]
	v_mfma_f32_16x16x32_bf16 v[70:73], v[160:163], v[216:219], v[70:73]
	v_mfma_f32_16x16x32_bf16 v[66:69], v[168:171], v[216:219], v[66:69]
	v_mfma_f32_16x16x32_bf16 v[118:121], v[164:167], v[180:183], v[118:121]
	v_mfma_f32_16x16x32_bf16 v[114:117], v[172:175], v[180:183], v[114:117]
	v_mfma_f32_16x16x32_bf16 v[102:105], v[164:167], v[188:191], v[102:105]
	v_mfma_f32_16x16x32_bf16 v[98:101], v[172:175], v[188:191], v[98:101]
	v_mfma_f32_16x16x32_bf16 v[86:89], v[164:167], v[212:215], v[86:89]
	v_mfma_f32_16x16x32_bf16 v[82:85], v[172:175], v[212:215], v[82:85]
	v_mfma_f32_16x16x32_bf16 v[70:73], v[164:167], v[220:223], v[70:73]
	v_mfma_f32_16x16x32_bf16 v[66:69], v[172:175], v[220:223], v[66:69]
	s_barrier
	s_add_i32 s40, s40, s59
	v_lshl_add_u64 v[140:141], s[26:27], 0, v[0:1]
	s_mov_b32 m0, s40
	ds_read_b128 v[176:179], v143 offset:16384
	ds_read_b128 v[180:183], v232 offset:16384
	ds_read_b128 v[184:187], v143 offset:18432
	ds_read_b128 v[188:191], v232 offset:18432
	ds_read_b128 v[208:211], v143 offset:20480
	ds_read_b128 v[212:215], v232 offset:20480
	ds_read_b128 v[216:219], v143 offset:22528
	ds_read_b128 v[220:223], v232 offset:22528
	global_load_lds_dwordx4 v[140:141], off
	s_add_i32 m0, s40, 0x2000
	s_add_u32 s40, s26, 0x80000
	v_lshl_add_u64 v[192:193], s[26:27], 0, v[130:131]
	s_addc_u32 s41, s27, 0
	s_add_i32 s42, s42, s59
	global_load_lds_dwordx4 v[192:193], off
	v_lshl_add_u64 v[224:225], s[40:41], 0, v[0:1]
	s_mov_b32 m0, s42
	v_lshl_add_u64 v[226:227], s[28:29], 0, v[132:133]
	global_load_lds_dwordx4 v[224:225], off
	v_lshl_add_u64 v[224:225], s[40:41], 0, v[130:131]
	s_add_i32 m0, s42, 0x2000
	s_nop 0
	global_load_lds_dwordx4 v[224:225], off
	v_lshl_add_u64 v[224:225], s[28:29], 0, v[134:135]
	s_mov_b32 m0, s34
	s_nop 0
	global_load_lds_dwordx4 v[224:225], off
	s_mov_b32 m0, s35
	s_nop 0
	global_load_lds_dwordx4 v[226:227], off
	s_waitcnt vmcnt(8)
	s_waitcnt lgkmcnt(0)
	s_barrier
; #define PG8_STAGE(bufoff, gbase, voff) do { _Pragma("unroll") for (int _i = 0; _i < 2; ++_i) \
;         __builtin_amdgcn_global_load_lds((const unsigned*)((const char*)(gbase) + (voff)[_i]), (PG8_LAS unsigned*)(lds + (bufoff) + ldsw + _i * 8192), 16, 0, 0); } while (0)
; #define PG8_LDA(dst, b, h) do { _Pragma("unroll") for (int m = 0; m < 4; ++m) _Pragma("unroll") for (int k = 0; k < 2; ++k) dst[m][k] = *(const PG8_LAS bf16x8*)(lds + PG8_SA(b, h) + aoff + m * 2048 + k * 1024); } while (0)
; #define PG8_LDB(dst, b, h) do { _Pragma("unroll") for (int n = 0; n < 2; ++n) _Pragma("unroll") for (int k = 0; k < 2; ++k) dst[n][k] = *(const PG8_LAS bf16x8*)(lds + PG8_SB(b, h) + boff + n * 2048 + k * 1024); } while (0)
; #define PG8_MMA(ai, bj, At, Bt) do { __builtin_amdgcn_s_setprio(1); _Pragma("unroll") for (int m = 0; m < 4; ++m) _Pragma("unroll") for (int n = 0; n < 2; ++n) _Pragma("unroll") for (int k = 0; k < 2; ++k) \
;         acc[ai][bj][m][n] = __builtin_amdgcn_mfma_f32_16x16x32_bf16(Bt[n][k], At[m][k], acc[ai][bj][m][n], 0, 0, 0); __builtin_amdgcn_s_setprio(0); } while (0)
; #define PG8_WAIT_V(n) asm volatile("s_waitcnt vmcnt(" #n ")" ::: "memory")
; #define PG8_WAIT_L(n) asm volatile("s_waitcnt lgkmcnt(" #n ")" ::: "memory")
; #define PG8_BAR __builtin_amdgcn_s_barrier()
; #define PG8_SCHED __builtin_amdgcn_sched_barrier(0)
; template <class Epi, class Sched, bool ALIGN_EPI = false, bool SP2 = false>
; __device__ __forceinline__ void gemm_phase(PG8_LAS unsigned char* lds, const Gemm g, const Sched& S, const Epi& E, int wid_in) {
;     ...
;             PG8_WAIT_V(8); PG8_WAIT_L(0); PG8_BAR; PG8_MMA(1, 0, At, B0); PG8_MMA(1, 1, At, B1); PG8_BAR; PG8_SCHED;
;             PG8_LDB(B0, 1, 0); PG8_LDB(B1, 1, 1); PG8_SCHED; PG8_LDA(At, 1, 0); PG8_STAGE(PG8_SA(0, 1), a2 + hstep, voffA);
;             PG8_WAIT_V(8); PG8_WAIT_L(0); PG8_BAR; PG8_MMA(0, 0, At, B0); PG8_MMA(0, 1, At, B1); PG8_BAR; PG8_SCHED;
	s_waitcnt lgkmcnt(0)
	v_mfma_f32_16x16x32_bf16 v[62:65], v[144:147], v[176:179], v[62:65]
	v_mfma_f32_16x16x32_bf16 v[58:61], v[152:155], v[176:179], v[58:61]
	v_mfma_f32_16x16x32_bf16 v[46:49], v[144:147], v[184:187], v[46:49]
	v_mfma_f32_16x16x32_bf16 v[42:45], v[152:155], v[184:187], v[42:45]
	v_mfma_f32_16x16x32_bf16 v[30:33], v[144:147], v[208:211], v[30:33]
	v_mfma_f32_16x16x32_bf16 v[26:29], v[152:155], v[208:211], v[26:29]
	v_mfma_f32_16x16x32_bf16 v[14:17], v[144:147], v[216:219], v[14:17]
	v_mfma_f32_16x16x32_bf16 v[10:13], v[152:155], v[216:219], v[10:13]
	v_mfma_f32_16x16x32_bf16 v[62:65], v[148:151], v[180:183], v[62:65]
	v_mfma_f32_16x16x32_bf16 v[58:61], v[156:159], v[180:183], v[58:61]
	v_mfma_f32_16x16x32_bf16 v[46:49], v[148:151], v[188:191], v[46:49]
	v_mfma_f32_16x16x32_bf16 v[42:45], v[156:159], v[188:191], v[42:45]
	v_mfma_f32_16x16x32_bf16 v[30:33], v[148:151], v[212:215], v[30:33]
	v_mfma_f32_16x16x32_bf16 v[26:29], v[156:159], v[212:215], v[26:29]
	v_mfma_f32_16x16x32_bf16 v[14:17], v[148:151], v[220:223], v[14:17]
	v_mfma_f32_16x16x32_bf16 v[10:13], v[156:159], v[220:223], v[10:13]
	v_mfma_f32_16x16x32_bf16 v[54:57], v[160:163], v[176:179], v[54:57]
	v_mfma_f32_16x16x32_bf16 v[50:53], v[168:171], v[176:179], v[50:53]
	v_mfma_f32_16x16x32_bf16 v[38:41], v[160:163], v[184:187], v[38:41]
	v_mfma_f32_16x16x32_bf16 v[34:37], v[168:171], v[184:187], v[34:37]
	v_mfma_f32_16x16x32_bf16 v[22:25], v[160:163], v[208:211], v[22:25]
	v_mfma_f32_16x16x32_bf16 v[18:21], v[168:171], v[208:211], v[18:21]
	v_mfma_f32_16x16x32_bf16 v[6:9], v[160:163], v[216:219], v[6:9]
	v_mfma_f32_16x16x32_bf16 v[2:5], v[168:171], v[216:219], v[2:5]
	v_mfma_f32_16x16x32_bf16 v[54:57], v[164:167], v[180:183], v[54:57]
	v_mfma_f32_16x16x32_bf16 v[50:53], v[172:175], v[180:183], v[50:53]
	v_mfma_f32_16x16x32_bf16 v[38:41], v[164:167], v[188:191], v[38:41]
	v_mfma_f32_16x16x32_bf16 v[34:37], v[172:175], v[188:191], v[34:37]
	v_mfma_f32_16x16x32_bf16 v[22:25], v[164:167], v[212:215], v[22:25]
	v_mfma_f32_16x16x32_bf16 v[18:21], v[172:175], v[212:215], v[18:21]
	v_mfma_f32_16x16x32_bf16 v[6:9], v[164:167], v[220:223], v[6:9]
	v_mfma_f32_16x16x32_bf16 v[2:5], v[172:175], v[220:223], v[2:5]
	s_barrier
	s_add_i32 s40, 0, 0x18000
	s_add_i32 s41, 0, 0x1c000
	v_add_u32_e32 v156, s40, v142
	v_add_u32_e32 v234, s40, v233
	v_add_u32_e32 v172, s41, v142
	v_add_u32_e32 v235, s41, v233
	ds_read_b128 v[144:147], v156
	ds_read_b128 v[148:151], v234
	ds_read_b128 v[152:155], v156 offset:2048
	ds_read_b128 v[156:159], v234 offset:2048
	ds_read_b128 v[160:163], v172
	ds_read_b128 v[164:167], v235
	ds_read_b128 v[168:171], v172 offset:2048
	ds_read_b128 v[172:175], v235 offset:2048
	s_add_u32 s28, s28, 0x80000
	s_addc_u32 s29, s29, 0
	s_mov_b32 m0, s36
	v_lshl_add_u64 v[228:229], s[28:29], 0, v[134:135]
	ds_read_b128 v[176:179], v143 offset:32768
	ds_read_b128 v[180:183], v232 offset:32768
	ds_read_b128 v[184:187], v143 offset:34816
	ds_read_b128 v[188:191], v232 offset:34816
	ds_read_b128 v[208:211], v143 offset:36864
	ds_read_b128 v[212:215], v232 offset:36864
	ds_read_b128 v[216:219], v143 offset:38912
	ds_read_b128 v[220:223], v232 offset:38912
	global_load_lds_dwordx4 v[228:229], off
	v_lshl_add_u64 v[228:229], s[28:29], 0, v[132:133]
	s_mov_b32 m0, s37
	s_nop 0
	global_load_lds_dwordx4 v[228:229], off
	s_waitcnt vmcnt(8)
	s_waitcnt lgkmcnt(0)
	s_barrier
	s_waitcnt lgkmcnt(0)
	v_mfma_f32_16x16x32_bf16 v[126:129], v[144:147], v[176:179], v[126:129]
	v_mfma_f32_16x16x32_bf16 v[122:125], v[152:155], v[176:179], v[122:125]
	v_mfma_f32_16x16x32_bf16 v[110:113], v[144:147], v[184:187], v[110:113]
	v_mfma_f32_16x16x32_bf16 v[106:109], v[152:155], v[184:187], v[106:109]
	v_mfma_f32_16x16x32_bf16 v[94:97], v[144:147], v[208:211], v[94:97]
	v_mfma_f32_16x16x32_bf16 v[90:93], v[152:155], v[208:211], v[90:93]
	v_mfma_f32_16x16x32_bf16 v[78:81], v[144:147], v[216:219], v[78:81]
	v_mfma_f32_16x16x32_bf16 v[74:77], v[152:155], v[216:219], v[74:77]
	v_mfma_f32_16x16x32_bf16 v[126:129], v[148:151], v[180:183], v[126:129]
	v_mfma_f32_16x16x32_bf16 v[122:125], v[156:159], v[180:183], v[122:125]
	v_mfma_f32_16x16x32_bf16 v[110:113], v[148:151], v[188:191], v[110:113]
	v_mfma_f32_16x16x32_bf16 v[106:109], v[156:159], v[188:191], v[106:109]
	v_mfma_f32_16x16x32_bf16 v[94:97], v[148:151], v[212:215], v[94:97]
	v_mfma_f32_16x16x32_bf16 v[90:93], v[156:159], v[212:215], v[90:93]
	v_mfma_f32_16x16x32_bf16 v[78:81], v[148:151], v[220:223], v[78:81]
	v_mfma_f32_16x16x32_bf16 v[74:77], v[156:159], v[220:223], v[74:77]
	v_mfma_f32_16x16x32_bf16 v[118:121], v[160:163], v[176:179], v[118:121]
	v_mfma_f32_16x16x32_bf16 v[114:117], v[168:171], v[176:179], v[114:117]
	v_mfma_f32_16x16x32_bf16 v[102:105], v[160:163], v[184:187], v[102:105]
	v_mfma_f32_16x16x32_bf16 v[98:101], v[168:171], v[184:187], v[98:101]
	v_mfma_f32_16x16x32_bf16 v[86:89], v[160:163], v[208:211], v[86:89]
	v_mfma_f32_16x16x32_bf16 v[82:85], v[168:171], v[208:211], v[82:85]
	v_mfma_f32_16x16x32_bf16 v[70:73], v[160:163], v[216:219], v[70:73]
	v_mfma_f32_16x16x32_bf16 v[66:69], v[168:171], v[216:219], v[66:69]
	v_mfma_f32_16x16x32_bf16 v[118:121], v[164:167], v[180:183], v[118:121]
	v_mfma_f32_16x16x32_bf16 v[114:117], v[172:175], v[180:183], v[114:117]
	v_mfma_f32_16x16x32_bf16 v[102:105], v[164:167], v[188:191], v[102:105]
	v_mfma_f32_16x16x32_bf16 v[98:101], v[172:175], v[188:191], v[98:101]
	v_mfma_f32_16x16x32_bf16 v[86:89], v[164:167], v[212:215], v[86:89]
	v_mfma_f32_16x16x32_bf16 v[82:85], v[172:175], v[212:215], v[82:85]
	v_mfma_f32_16x16x32_bf16 v[70:73], v[164:167], v[220:223], v[70:73]
	v_mfma_f32_16x16x32_bf16 v[66:69], v[172:175], v[220:223], v[66:69]
	s_barrier
; #define PG8_STAGE(bufoff, gbase, voff) do { _Pragma("unroll") for (int _i = 0; _i < 2; ++_i) \
;         __builtin_amdgcn_global_load_lds((const unsigned*)((const char*)(gbase) + (voff)[_i]), (PG8_LAS unsigned*)(lds + (bufoff) + ldsw + _i * 8192), 16, 0, 0); } while (0)
; #define PG8_LDA(dst, b, h) do { _Pragma("unroll") for (int m = 0; m < 4; ++m) _Pragma("unroll") for (int k = 0; k < 2; ++k) dst[m][k] = *(const PG8_LAS bf16x8*)(lds + PG8_SA(b, h) + aoff + m * 2048 + k * 1024); } while (0)
; #define PG8_MMA(ai, bj, At, Bt) do { __builtin_amdgcn_s_setprio(1); _Pragma("unroll") for (int m = 0; m < 4; ++m) _Pragma("unroll") for (int n = 0; n < 2; ++n) _Pragma("unroll") for (int k = 0; k < 2; ++k) \
;         acc[ai][bj][m][n] = __builtin_amdgcn_mfma_f32_16x16x32_bf16(Bt[n][k], At[m][k], acc[ai][bj][m][n], 0, 0, 0); __builtin_amdgcn_s_setprio(0); } while (0)
; #define PG8_WAIT_V(n) asm volatile("s_waitcnt vmcnt(" #n ")" ::: "memory")
; #define PG8_WAIT_L(n) asm volatile("s_waitcnt lgkmcnt(" #n ")" ::: "memory")
; #define PG8_BAR __builtin_amdgcn_s_barrier()
; #define PG8_SCHED __builtin_amdgcn_sched_barrier(0)
; template <class Epi, class Sched, bool ALIGN_EPI = false, bool SP2 = false>
; __device__ __forceinline__ void gemm_phase(PG8_LAS unsigned char* lds, const Gemm g, const Sched& S, const Epi& E, int wid_in) {
;     ...
;         for (int t = 0; t < nt; t += 2) {
;             const bool last = (t == nt - 2);
;             const char* a1 = cA + (size_t)(t + 1) * kstep;
;             const char* a2 = last ? nA : cA + (size_t)(t + 2) * kstep; const char* b2 = last ? nB : cB + (size_t)(t + 2) * kstep;
;     ...
;             PG8_LDA(At, 1, 1); PG8_STAGE(PG8_SB(1, 0), b3, voffB); PG8_STAGE(PG8_SB(1, 1), b3 + hstep, voffB); PG8_STAGE(PG8_SA(1, 0), a3, voffA);
;             PG8_WAIT_V(8); PG8_WAIT_L(0); PG8_BAR; PG8_MMA(1, 0, At, B0); PG8_MMA(1, 1, At, B1); PG8_BAR; PG8_SCHED;
	s_add_i32 s28, s40, s59
	v_lshl_add_u64 v[140:141], v[140:141], 0, s[94:95]
	s_mov_b32 m0, s28
	ds_read_b128 v[176:179], v143 offset:49152
	ds_read_b128 v[180:183], v232 offset:49152
	ds_read_b128 v[184:187], v143 offset:51200
	ds_read_b128 v[188:191], v232 offset:51200
	ds_read_b128 v[208:211], v143 offset:53248
	ds_read_b128 v[212:215], v232 offset:53248
	ds_read_b128 v[216:219], v143 offset:55296
	ds_read_b128 v[220:223], v232 offset:55296
	global_load_lds_dwordx4 v[140:141], off
	s_add_i32 m0, s28, 0x2000
	s_add_u32 s26, s26, 0x80080
	v_lshl_add_u64 v[140:141], v[192:193], 0, s[94:95]
	s_addc_u32 s27, s27, 0
	s_add_i32 s28, s41, s59
	global_load_lds_dwordx4 v[140:141], off
	v_lshl_add_u64 v[140:141], s[26:27], 0, v[0:1]
	s_mov_b32 m0, s28
	s_nop 0
	global_load_lds_dwordx4 v[140:141], off
	v_lshl_add_u64 v[140:141], s[26:27], 0, v[130:131]
	s_add_i32 m0, s28, 0x2000
	s_nop 0
	global_load_lds_dwordx4 v[140:141], off
	v_lshl_add_u64 v[140:141], v[224:225], 0, s[94:95]
	s_mov_b32 m0, s48
	s_nop 0
	global_load_lds_dwordx4 v[140:141], off
	v_lshl_add_u64 v[140:141], v[226:227], 0, s[94:95]
	s_mov_b32 m0, s52
	s_nop 0
	global_load_lds_dwordx4 v[140:141], off
	s_waitcnt vmcnt(8)
	s_waitcnt lgkmcnt(0)
	s_barrier
	s_waitcnt lgkmcnt(0)
	v_mfma_f32_16x16x32_bf16 v[62:65], v[144:147], v[176:179], v[62:65]
	v_mfma_f32_16x16x32_bf16 v[58:61], v[152:155], v[176:179], v[58:61]
	v_mfma_f32_16x16x32_bf16 v[46:49], v[144:147], v[184:187], v[46:49]
	v_mfma_f32_16x16x32_bf16 v[42:45], v[152:155], v[184:187], v[42:45]
	v_mfma_f32_16x16x32_bf16 v[30:33], v[144:147], v[208:211], v[30:33]
	v_mfma_f32_16x16x32_bf16 v[26:29], v[152:155], v[208:211], v[26:29]
	v_mfma_f32_16x16x32_bf16 v[14:17], v[144:147], v[216:219], v[14:17]
	v_mfma_f32_16x16x32_bf16 v[10:13], v[152:155], v[216:219], v[10:13]
	v_mfma_f32_16x16x32_bf16 v[62:65], v[148:151], v[180:183], v[62:65]
	v_mfma_f32_16x16x32_bf16 v[58:61], v[156:159], v[180:183], v[58:61]
	v_mfma_f32_16x16x32_bf16 v[46:49], v[148:151], v[188:191], v[46:49]
	v_mfma_f32_16x16x32_bf16 v[42:45], v[156:159], v[188:191], v[42:45]
	v_mfma_f32_16x16x32_bf16 v[30:33], v[148:151], v[212:215], v[30:33]
	v_mfma_f32_16x16x32_bf16 v[26:29], v[156:159], v[212:215], v[26:29]
	v_mfma_f32_16x16x32_bf16 v[14:17], v[148:151], v[220:223], v[14:17]
	v_mfma_f32_16x16x32_bf16 v[10:13], v[156:159], v[220:223], v[10:13]
	v_mfma_f32_16x16x32_bf16 v[54:57], v[160:163], v[176:179], v[54:57]
	v_mfma_f32_16x16x32_bf16 v[50:53], v[168:171], v[176:179], v[50:53]
	v_mfma_f32_16x16x32_bf16 v[38:41], v[160:163], v[184:187], v[38:41]
	v_mfma_f32_16x16x32_bf16 v[34:37], v[168:171], v[184:187], v[34:37]
	v_mfma_f32_16x16x32_bf16 v[22:25], v[160:163], v[208:211], v[22:25]
	v_mfma_f32_16x16x32_bf16 v[18:21], v[168:171], v[208:211], v[18:21]
	v_mfma_f32_16x16x32_bf16 v[6:9], v[160:163], v[216:219], v[6:9]
	v_mfma_f32_16x16x32_bf16 v[2:5], v[168:171], v[216:219], v[2:5]
	v_mfma_f32_16x16x32_bf16 v[54:57], v[164:167], v[180:183], v[54:57]
	v_mfma_f32_16x16x32_bf16 v[50:53], v[172:175], v[180:183], v[50:53]
	v_mfma_f32_16x16x32_bf16 v[38:41], v[164:167], v[188:191], v[38:41]
	v_mfma_f32_16x16x32_bf16 v[34:37], v[172:175], v[188:191], v[34:37]
	v_mfma_f32_16x16x32_bf16 v[22:25], v[164:167], v[212:215], v[22:25]
	v_mfma_f32_16x16x32_bf16 v[18:21], v[172:175], v[212:215], v[18:21]
	v_mfma_f32_16x16x32_bf16 v[6:9], v[164:167], v[220:223], v[6:9]
	v_mfma_f32_16x16x32_bf16 v[2:5], v[172:175], v[220:223], v[2:5]
	s_barrier
	s_add_i32 s73, s73, 2
	s_add_u32 s72, s72, 0x100
	s_addc_u32 s63, s63, 0
	s_add_u32 s24, s24, 0x100
	s_addc_u32 s25, s25, 0
	s_cmp_gt_u32 s73, 29
	s_cbranch_scc0 .LBB0_1153
	s_setprio 0
	s_and_b64 vcc, exec, s[14:15]
	s_cbranch_vccz .LBB0_1156
	s_barrier
